# pass C items remapped so the 8 segments of a sequence share an XCD L2 (segment-state fold hits L2); GLA A1 pipelined; P4 epilogue loads batched; early L2 writeback at the P2a barrier
# speedup vs baseline: 1.0135x; 1.0056x over previous
; __global__ void __launch_bounds__(512) mk_fwd(Args a) {
;     ...
;         if (PH_MASK & 64) for (int it = blk; it < 32 * GLA_NSEG; it += G) { const int seq = it / GLA_NSEG, seg = it % GLA_NSEG;
;             gla_seg<true>(seq >> 2, seq & 3, seg, QKp, GVp, GGp, ALR, P.w_alpha2, P.b_alpha, P.gla_norm, OGLA, Lws, Dws, lds, tid); }
.LBB0_427:
	s_or_b64 exec, exec, s[0:1]
	s_add_u32 s36, s68, 0xa800000
	s_addc_u32 s37, s69, 0
	v_readlane_b32 s74, v246, 3
	s_cmpk_gt_i32 s2, 0xff
	v_readlane_b32 s75, v246, 4
	s_waitcnt lgkmcnt(0)
	s_barrier
	s_cbranch_scc1 .LBB0_494
	s_add_u32 s38, s68, 0x1c843c00
	s_addc_u32 s39, s69, 0
	s_add_u32 s33, s68, 0x2601000
	s_addc_u32 s80, s69, 0
	s_add_u32 s40, s68, 0x2800400
	s_addc_u32 s41, s69, 0
	s_add_u32 s42, s68, 0x6800100
	s_addc_u32 s43, s69, 0
	s_mov_b32 s45, 0
	v_mov_b32_e32 v1, 0
	s_mov_b64 s[46:47], 0x40000
	s_movk_i32 s81, 0x100
	s_movk_i32 s82, 0x210
	s_add_i32 s83, 0, 0x11000
	s_add_i32 s84, 0, 0x21400
	s_add_i32 s85, 0, 0x15800
	s_movk_i32 s86, 0x110
	s_movk_i32 s87, 0x90
	s_add_i32 s88, 0, 0x1e800
	s_add_i32 s89, 0, 0x20c00
	s_movk_i32 s90, 0x220
	s_mov_b32 s91, 0xbfb8aa3b
	v_mov_b32_e32 v206, 0x358637bd
	s_mov_b64 s[48:49], 0x1000
	v_mbcnt_hi_u32_b32 v207, -1, v205
	s_and_b32 s0, s2, 7
	s_lshl_b32 s0, s0, 5
	s_bfe_u32 s1, s2, 0x20003
	s_lshl_b32 s1, s1, 3
	s_or_b32 s0, s0, s1
	s_lshr_b32 s1, s2, 5
	s_or_b32 s0, s0, s1
	s_cmpk_eq_i32 s70, 0x100
	s_cselect_b32 s94, s0, s2
	s_branch .LBB0_430
